# prep loop: in-row part of the sum-of-squares reduction via DPP row_ror 8/4/2/1 instead of 4 ds_bpermute round trips
# baseline (speedup 1.0000x reference)
.LBB0_877:
	v_pk_mul_f32 v[212:213], v[144:145], v[144:145]
	v_pk_mul_f32 v[214:215], v[140:141], v[140:141]
	v_pk_mul_f32 v[204:205], v[216:217], v[216:217]
	v_pk_mul_f32 v[208:209], v[146:147], v[146:147]
	v_pk_mul_f32 v[210:211], v[142:143], v[142:143]
	v_mov_b32_e32 v216, v212
	v_mov_b32_e32 v217, v214
	v_mov_b32_e32 v214, v213
	v_mov_b32_e32 v212, v208
	v_mov_b32_e32 v213, v210
	v_mov_b32_e32 v210, v209
	v_pk_add_f32 v[208:209], v[216:217], v[214:215]
	v_pk_mul_f32 v[206:207], v[136:137], v[136:137]
	v_pk_add_f32 v[208:209], v[212:213], v[208:209]
	v_pk_mul_f32 v[200:201], v[218:219], v[218:219]
	v_pk_mul_f32 v[202:203], v[138:139], v[138:139]
	v_pk_add_f32 v[208:209], v[210:211], v[208:209]
	v_mov_b32_e32 v210, v204
	v_mov_b32_e32 v211, v206
	v_mov_b32_e32 v206, v205
	v_mov_b32_e32 v204, v200
	v_mov_b32_e32 v205, v202
	v_mov_b32_e32 v202, v201
	v_pk_add_f32 v[200:201], v[210:211], v[206:207]
	v_add_u32_e32 v206, s5, v148
	v_pk_add_f32 v[200:201], v[204:205], v[200:201]
	v_xor_b32_e32 v215, 0x80000000, v7
	v_pk_add_f32 v[200:201], v[202:203], v[200:201]
	v_add_f32_e32 v202, v208, v209
	v_add_f32_e32 v201, v201, v202
	v_add_f32_e32 v200, v200, v201
	ds_bpermute_b32 v201, v149, v200
	v_xor_b32_e32 v214, 0x80000000, v6
	v_ashrrev_i32_e32 v207, 31, v206
	s_waitcnt lgkmcnt(0)
	v_add_f32_e32 v200, v200, v201
	ds_bpermute_b32 v201, v161, v200
	s_waitcnt lgkmcnt(0)
	v_add_f32_e32 v200, v200, v201
	s_nop 1
	v_add_f32_dpp v200, v200, v200 row_ror:8 row_mask:0xf bank_mask:0xf
	s_nop 1
	v_add_f32_dpp v200, v200, v200 row_ror:4 row_mask:0xf bank_mask:0xf
	s_nop 1
	v_add_f32_dpp v200, v200, v200 row_ror:2 row_mask:0xf bank_mask:0xf
	s_nop 1
	v_add_f32_dpp v200, v200, v200 row_ror:1 row_mask:0xf bank_mask:0xf
	v_fmamk_f32 v200, v200, 0x3a800000, v221
	v_mul_f32_e32 v201, 0x4b800000, v200
	v_cmp_gt_f32_e32 vcc, s80, v200
	s_nop 1
	v_cndmask_b32_e32 v200, v200, v201, vcc
	v_rsq_f32_e32 v208, v200
	v_lshlrev_b64 v[200:201], 11, v[206:207]
	v_lshl_add_u64 v[204:205], v[150:151], 0, v[200:201]
	v_lshl_add_u64 v[202:203], v[152:153], 0, v[200:201]
	v_mul_f32_e32 v209, 0x45800000, v208
	v_cndmask_b32_e32 v208, v208, v209, vcc
	v_pk_mul_f32 v[210:211], v[144:145], v[208:209] op_sel_hi:[1,0]
	v_pk_mul_f32 v[212:213], v[146:147], v[208:209] op_sel_hi:[1,0]
	v_pk_mul_f32 v[144:145], v[4:5], v[210:211]
	v_pk_mul_f32 v[146:147], v[6:7], v[212:213]
	v_pk_fma_f32 v[134:135], v[214:215], v[212:213], v[134:135]
	v_pk_fma_f32 v[132:133], v[4:5], v[210:211], v[132:133] neg_lo:[1,0,0] neg_hi:[1,0,0]
	v_pk_fma_f32 v[210:211], v[22:23], v[134:135], v[146:147]
	v_pk_fma_f32 v[212:213], v[20:21], v[132:133], v[144:145]
	s_and_b64 vcc, exec, s[18:19]
	v_cvt_pk_bf16_f32 v212, v212, v213
	v_cvt_pk_bf16_f32 v213, v210, v211
	global_store_dwordx2 v[204:205], v[212:213], off
	s_cbranch_vccz .LBB0_879
	v_pk_fma_f32 v[210:211], v[50:51], v[134:135], v[146:147]
	v_pk_fma_f32 v[212:213], v[48:49], v[132:133], v[144:145]
	s_nop 0
	v_cvt_pk_bf16_f32 v212, v212, v213
	v_cvt_pk_bf16_f32 v213, v210, v211
	global_store_dwordx2 v[202:203], v[212:213], off
